# retention scan: one static s_setprio 1 for waves 4-7 (the younger wave of each SIMD pair) for the duration of the scan
# baseline (speedup 1.0000x reference)
.LBB0_1313:
	s_or_b64 exec, exec, s[0:1]
	s_add_u32 s6, s94, 0x2a402800
	s_addc_u32 s7, s95, 0
	s_cmpk_gt_u32 s2, 0x7f
	s_waitcnt lgkmcnt(0)
	s_barrier
	s_cbranch_scc1 .LBB0_1326
	s_and_b32 s76, s2, 7
	s_lshr_b32 s77, s2, 3
	s_lshr_b32 s78, s77, 3
	s_lshl_b32 s72, s76, 1
	s_add_u32 s72, s72, s78
	s_and_b32 s73, s77, 7
	s_lshr_b32 s74, s72, 2
	s_and_b32 s75, s72, 3
	s_mov_b32 s82, 0xbd020aec
	s_cmp_eq_u32 s75, 1
	s_cselect_b32 s82, 0xbc8102b3, s82
	s_cmp_eq_u32 s75, 2
	s_cselect_b32 s82, 0xbc0080ac, s82
	s_cmp_eq_u32 s75, 3
	s_cselect_b32 s82, 0xbb80402b, s82
	v_lshrrev_b32_e32 v210, 6, v198
	v_and_b32_e32 v211, 15, v198
	v_bfe_u32 v212, v198, 4, 2
	v_readfirstlane_b32 s71, v210
	v_lshl_or_b32 v213, v210, 4, v211
	v_add_u32_e32 v213, 1, v213
	v_cvt_f32_i32_e32 v213, v213
	v_mul_f32_e32 v213, s82, v213
	v_mul_f32_e32 v213, 0x3fb8aa3b, v213
	v_exp_f32_e32 v202, v213
	v_mov_b32_e32 v213, 0x43000000
	v_mul_f32_e32 v213, s82, v213
	v_mul_f32_e32 v213, 0x3fb8aa3b, v213
	v_exp_f32_e32 v204, v213
	s_nop 1
	v_mov_b32_e32 v203, v202
	v_mov_b32_e32 v205, v204
	v_lshlrev_b32_e32 v192, 4, v211
	v_lshl_add_u32 v192, v212, 8, v192
	v_lshlrev_b32_e32 v193, 11, v211
	v_lshl_add_u32 v193, v212, 4, v193
	v_and_b32_e32 v213, 63, v198
	v_lshrrev_b32_e32 v195, 3, v213
	v_and_b32_e32 v215, 7, v213
	v_mul_u32_u24_e32 v214, 144, v195
	v_lshl_add_u32 v215, v215, 4, v214
	v_and_b32_e32 v214, 7, v213
	v_lshlrev_b32_e32 v195, 12, v195
	v_lshl_add_u32 v195, v214, 4, v195
	v_add_u32_e32 v220, 0x8000, v195
	v_mul_u32_u24_e32 v214, 144, v211
	v_lshl_add_u32 v214, v212, 3, v214
	v_mul_u32_u24_e32 v213, 2304, v210
	v_add_u32_e32 v213, 102400, v213
	v_add_u32_e32 v214, v214, v213
	v_add_u32_e32 v215, v215, v213
	v_lshrrev_b32_e32 v213, 3, v198
	v_and_b32_e32 v194, 7, v198
	v_lshlrev_b32_e32 v194, 4, v194
	v_lshrrev_b32_e32 v218, 2, v213
	v_lshrrev_b32_e32 v219, 3, v213
	v_xor_b32_e32 v218, v218, v219
	v_and_b32_e32 v218, 1, v218
	v_and_b32_e32 v219, 7, v198
	v_xor_b32_e32 v219, v219, v218
	v_mul_u32_u24_e32 v201, 272, v213
	v_lshl_add_u32 v201, v219, 4, v201
	v_lshrrev_b32_e32 v216, 2, v211
	v_lshrrev_b32_e32 v217, 3, v211
	v_xor_b32_e32 v216, v216, v217
	v_and_b32_e32 v216, 1, v216
	v_xor_b32_e32 v217, v212, v216
	v_lshlrev_b32_e32 v218, 3, v212
	v_lshlrev_b32_e32 v216, 4, v216
	v_xor_b32_e32 v218, v218, v216
	v_lshl_add_u32 v194, v213, 13, v194
	v_add_u32_e32 v201, 67584, v201
	v_mul_u32_u24_e32 v196, 528, v211
	v_add_u32_e32 v200, v218, v196
	v_lshl_add_u32 v200, v210, 6, v200
	v_add_u32_e32 v200, 33792, v200
	v_lshl_add_u32 v196, v217, 4, v196
	v_mul_u32_u24_e32 v197, 272, v211
	v_lshl_add_u32 v197, v217, 4, v197
	v_add_u32_e32 v197, 67584, v197
	v_lshlrev_b32_e32 v206, 13, v212
	v_lshl_add_u32 v206, v211, 2, v206
	v_add_u32_e32 v207, 2048, v206
	v_add_u32_e32 v208, 4096, v206
	v_add_u32_e32 v209, 6144, v206
	s_mov_b32 s76, 0x27402800
	s_lshl_b32 s77, s72, 20
	s_add_u32 s76, s76, s77
	s_lshl_b32 s77, s71, 12
	s_add_u32 s76, s76, s77
	s_add_u32 s62, s94, s76
	s_addc_u32 s63, s95, 0
	s_mov_b32 s76, 0x28403800
	s_lshl_b32 s77, s72, 21
	s_add_u32 s76, s76, s77
	s_lshl_b32 s77, s71, 13
	s_add_u32 s76, s76, s77
	s_add_u32 s64, s94, s76
	s_addc_u32 s65, s95, 0
	s_mov_b32 s76, 0x1a802800
	s_lshl_b32 s77, s74, 23
	s_add_u32 s76, s76, s77
	s_lshl_b32 s77, s71, 15
	s_add_u32 s76, s76, s77
	s_lshl_b32 s77, s75, 9
	s_add_u32 s76, s76, s77
	s_add_u32 s60, s94, s76
	s_addc_u32 s61, s95, 0
	s_mov_b32 s76, 0x23002800
	s_lshl_b32 s77, s72, 22
	s_add_u32 s76, s76, s77
	s_lshl_b32 s77, s73, 19
	s_add_u32 s76, s76, s77
	s_add_u32 s66, s94, s76
	s_addc_u32 s67, s95, 0
	s_mov_b32 s76, 0x2a402800
	s_lshl_b32 s77, s74, 24
	s_add_u32 s76, s76, s77
	s_lshl_b32 s77, s71, 16
	s_add_u32 s76, s76, s77
	s_lshl_b32 s77, s75, 10
	s_add_u32 s76, s76, s77
	s_lshl_b32 s77, s73, 7
	s_add_u32 s76, s76, s77
	s_add_u32 s68, s94, s76
	s_addc_u32 s69, s95, 0
	s_mov_b32 s76, 0x6500000
	s_lshl_b32 s77, s72, 19
	s_add_u32 s76, s76, s77
	s_lshl_b32 s77, s71, 16
	s_add_u32 s76, s76, s77
	s_lshl_b32 s77, s73, 8
	s_add_u32 s76, s76, s77
	s_add_u32 s44, s92, s76
	s_addc_u32 s45, s93, 0
	s_add_u32 s46, s44, 0x8000
	s_addc_u32 s47, s45, 0
	global_load_dwordx4 v[176:179], v194, s[66:67]
	global_load_dwordx4 v[180:183], v194, s[66:67] offset:128
	global_load_dwordx4 v[0:3], v193, s[60:61]
	global_load_dwordx4 v[4:7], v193, s[60:61] offset:64
	global_load_dwordx4 v[8:11], v193, s[60:61] offset:128
	global_load_dwordx4 v[12:15], v193, s[60:61] offset:192
	global_load_dwordx4 v[16:19], v193, s[60:61] offset:256
	global_load_dwordx4 v[20:23], v193, s[60:61] offset:320
	global_load_dwordx4 v[24:27], v193, s[60:61] offset:384
	global_load_dwordx4 v[28:31], v193, s[60:61] offset:448
	global_load_dwordx4 v[32:35], v192, s[62:63]
	global_load_dwordx4 v[36:39], v192, s[62:63] offset:1024
	global_load_dwordx4 v[40:43], v192, s[62:63] offset:2048
	global_load_dwordx4 v[44:47], v192, s[62:63] offset:3072
	global_load_dwordx4 v[48:51], v192, s[64:65] offset:-4096
	global_load_dwordx4 v[64:67], v192, s[64:65]
	global_load_dwordx4 v[52:55], v192, s[64:65] offset:-3072
	global_load_dwordx4 v[68:71], v192, s[64:65] offset:1024
	global_load_dwordx4 v[56:59], v192, s[64:65] offset:-2048
	global_load_dwordx4 v[72:75], v192, s[64:65] offset:2048
	global_load_dwordx4 v[60:63], v192, s[64:65] offset:-1024
	global_load_dwordx4 v[76:79], v192, s[64:65] offset:3072
	v_mov_b32_e32 v216, 0
	v_mov_b32_e32 v217, 0
	v_mov_b32_e32 v218, 0
	v_mov_b32_e32 v219, 0
	v_mov_b32_e32 v80, 0
	v_mov_b32_e32 v81, 0
	v_mov_b32_e32 v82, 0
	v_mov_b32_e32 v83, 0
	v_mov_b32_e32 v84, 0
	v_mov_b32_e32 v85, 0
	v_mov_b32_e32 v86, 0
	v_mov_b32_e32 v87, 0
	v_mov_b32_e32 v88, 0
	v_mov_b32_e32 v89, 0
	v_mov_b32_e32 v90, 0
	v_mov_b32_e32 v91, 0
	v_mov_b32_e32 v92, 0
	v_mov_b32_e32 v93, 0
	v_mov_b32_e32 v94, 0
	v_mov_b32_e32 v95, 0
	v_mov_b32_e32 v96, 0
	v_mov_b32_e32 v97, 0
	v_mov_b32_e32 v98, 0
	v_mov_b32_e32 v99, 0
	v_mov_b32_e32 v100, 0
	v_mov_b32_e32 v101, 0
	v_mov_b32_e32 v102, 0
	v_mov_b32_e32 v103, 0
	v_mov_b32_e32 v104, 0
	v_mov_b32_e32 v105, 0
	v_mov_b32_e32 v106, 0
	v_mov_b32_e32 v107, 0
	v_mov_b32_e32 v108, 0
	v_mov_b32_e32 v109, 0
	v_mov_b32_e32 v110, 0
	v_mov_b32_e32 v111, 0
	v_lshlrev_b32_e32 v213, 4, v198
	ds_write_b128 v213, v[216:219] offset:0
	ds_write_b128 v213, v[216:219] offset:8192
	ds_write_b128 v213, v[216:219] offset:16384
	ds_write_b128 v213, v[216:219] offset:24576
	ds_write_b128 v213, v[216:219] offset:32768
	s_waitcnt vmcnt(20)
	ds_write_b128 v201, v[176:179]
	ds_write_b128 v201, v[180:183] offset:128
	v_add_u32_e32 v201, 17408, v201
	s_add_u32 s60, s60, 0x40000
	s_addc_u32 s61, s61, 0
	s_add_u32 s62, s62, 0x8000
	s_addc_u32 s63, s63, 0
	s_add_u32 s64, s64, 0x10000
	s_addc_u32 s65, s65, 0
	s_add_u32 s66, s66, 0x100
	s_addc_u32 s67, s67, 0
	global_load_dwordx4 v[230:233], v193, s[60:61]
	global_load_dwordx4 v[234:237], v193, s[60:61] offset:64
	global_load_dwordx4 v[238:241], v193, s[60:61] offset:128
	global_load_dwordx4 v[242:245], v193, s[60:61] offset:192
	global_load_dwordx4 v[246:249], v193, s[60:61] offset:256
	global_load_dwordx4 v[250:253], v193, s[60:61] offset:320
	global_load_dwordx4 v[184:187], v193, s[60:61] offset:384
	global_load_dwordx4 v[188:191], v193, s[60:61] offset:448
	global_load_dwordx4 v[128:131], v192, s[62:63]
	global_load_dwordx4 v[132:135], v192, s[62:63] offset:1024
	global_load_dwordx4 v[136:139], v192, s[62:63] offset:2048
	global_load_dwordx4 v[140:143], v192, s[62:63] offset:3072
	s_add_u32 s60, s60, 0x40000
	s_addc_u32 s61, s61, 0
	s_add_u32 s62, s62, 0x8000
	s_addc_u32 s63, s63, 0
	global_load_dwordx4 v[222:225], v194, s[66:67]
	global_load_dwordx4 v[226:229], v194, s[66:67] offset:128
	s_add_u32 s66, s66, 0x100
	s_addc_u32 s67, s67, 0
	s_mov_b32 s70, 0
	s_mov_b32 s80, 33792
	s_mov_b32 s81, 17408
	s_waitcnt vmcnt(0) lgkmcnt(0)
	s_barrier
	s_cmp_lt_u32 s71, 4
	s_cbranch_scc1 .Lscan_noprio
	s_setprio 1
.Lscan_noprio:
.Lscan_chunk:
	global_load_dwordx4 v[176:179], v194, s[66:67]
	global_load_dwordx4 v[180:183], v194, s[66:67] offset:128
	ds_read_b128 v[144:147], v196 offset:0
	ds_read_b128 v[148:151], v196 offset:8448
	ds_read_b128 v[152:155], v196 offset:16896
	ds_read_b128 v[156:159], v196 offset:25344
	ds_read_b128 v[160:163], v196 offset:64
	ds_read_b128 v[164:167], v196 offset:8512
	ds_read_b128 v[168:171], v196 offset:16960
	s_waitcnt lgkmcnt(6)
	s_waitcnt vmcnt(47)
	v_mfma_f32_16x16x32_bf16 v[112:115], v[144:147], v[0:3], 0
	ds_read_b128 v[172:175], v196 offset:25408
	s_waitcnt lgkmcnt(6)
	v_mfma_f32_16x16x32_bf16 v[116:119], v[148:151], v[0:3], 0
	ds_read_b128 v[144:147], v196 offset:128
	s_waitcnt lgkmcnt(6)
	v_mfma_f32_16x16x32_bf16 v[120:123], v[152:155], v[0:3], 0
	ds_read_b128 v[148:151], v196 offset:8576
	s_waitcnt lgkmcnt(6)
	v_mfma_f32_16x16x32_bf16 v[124:127], v[156:159], v[0:3], 0
	global_load_dwordx4 v[0:3], v193, s[60:61]
	ds_read_b128 v[152:155], v196 offset:17024
	s_waitcnt lgkmcnt(6)
	s_waitcnt vmcnt(47)
	v_mfma_f32_16x16x32_bf16 v[112:115], v[160:163], v[4:7], v[112:115]
	ds_read_b128 v[156:159], v196 offset:25472
	s_waitcnt lgkmcnt(6)
	v_mfma_f32_16x16x32_bf16 v[116:119], v[164:167], v[4:7], v[116:119]
	ds_read_b128 v[160:163], v196 offset:192
	s_waitcnt lgkmcnt(6)
	v_mfma_f32_16x16x32_bf16 v[120:123], v[168:171], v[4:7], v[120:123]
	ds_read_b128 v[164:167], v196 offset:8640
	s_waitcnt lgkmcnt(6)
	v_mfma_f32_16x16x32_bf16 v[124:127], v[172:175], v[4:7], v[124:127]
	global_load_dwordx4 v[4:7], v193, s[60:61] offset:64
	ds_read_b128 v[168:171], v196 offset:17088
	s_waitcnt lgkmcnt(6)
	s_waitcnt vmcnt(47)
	v_mfma_f32_16x16x32_bf16 v[112:115], v[144:147], v[8:11], v[112:115]
	ds_read_b128 v[172:175], v196 offset:25536
	s_waitcnt lgkmcnt(6)
	v_mfma_f32_16x16x32_bf16 v[116:119], v[148:151], v[8:11], v[116:119]
	ds_read_b128 v[144:147], v196 offset:256
	s_waitcnt lgkmcnt(6)
	v_mfma_f32_16x16x32_bf16 v[120:123], v[152:155], v[8:11], v[120:123]
	ds_read_b128 v[148:151], v196 offset:8704
	s_waitcnt lgkmcnt(6)
	v_mfma_f32_16x16x32_bf16 v[124:127], v[156:159], v[8:11], v[124:127]
	global_load_dwordx4 v[8:11], v193, s[60:61] offset:128
	ds_read_b128 v[152:155], v196 offset:17152
	s_waitcnt lgkmcnt(6)
	s_waitcnt vmcnt(47)
	v_mfma_f32_16x16x32_bf16 v[112:115], v[160:163], v[12:15], v[112:115]
	ds_read_b128 v[156:159], v196 offset:25600
	s_waitcnt lgkmcnt(6)
	v_mfma_f32_16x16x32_bf16 v[116:119], v[164:167], v[12:15], v[116:119]
	ds_read_b128 v[160:163], v196 offset:320
	s_waitcnt lgkmcnt(6)
	v_mfma_f32_16x16x32_bf16 v[120:123], v[168:171], v[12:15], v[120:123]
	ds_read_b128 v[164:167], v196 offset:8768
	s_waitcnt lgkmcnt(6)
	v_mfma_f32_16x16x32_bf16 v[124:127], v[172:175], v[12:15], v[124:127]
	global_load_dwordx4 v[12:15], v193, s[60:61] offset:192
	ds_read_b128 v[168:171], v196 offset:17216
	s_waitcnt lgkmcnt(6)
	s_waitcnt vmcnt(47)
	v_mfma_f32_16x16x32_bf16 v[112:115], v[144:147], v[16:19], v[112:115]
	ds_read_b128 v[172:175], v196 offset:25664
	s_waitcnt lgkmcnt(6)
	v_mfma_f32_16x16x32_bf16 v[116:119], v[148:151], v[16:19], v[116:119]
	ds_read_b128 v[144:147], v196 offset:384
	s_waitcnt lgkmcnt(6)
	v_mfma_f32_16x16x32_bf16 v[120:123], v[152:155], v[16:19], v[120:123]
	ds_read_b128 v[148:151], v196 offset:8832
	s_waitcnt lgkmcnt(6)
	v_mfma_f32_16x16x32_bf16 v[124:127], v[156:159], v[16:19], v[124:127]
	global_load_dwordx4 v[16:19], v193, s[60:61] offset:256
	ds_read_b128 v[152:155], v196 offset:17280
	s_waitcnt lgkmcnt(6)
	s_waitcnt vmcnt(47)
	v_mfma_f32_16x16x32_bf16 v[112:115], v[160:163], v[20:23], v[112:115]
	ds_read_b128 v[156:159], v196 offset:25728
	s_waitcnt lgkmcnt(6)
	v_mfma_f32_16x16x32_bf16 v[116:119], v[164:167], v[20:23], v[116:119]
	ds_read_b128 v[160:163], v196 offset:448
	s_waitcnt lgkmcnt(6)
	v_mfma_f32_16x16x32_bf16 v[120:123], v[168:171], v[20:23], v[120:123]
	ds_read_b128 v[164:167], v196 offset:8896
	s_waitcnt lgkmcnt(6)
	v_mfma_f32_16x16x32_bf16 v[124:127], v[172:175], v[20:23], v[124:127]
	global_load_dwordx4 v[20:23], v193, s[60:61] offset:320
	ds_read_b128 v[168:171], v196 offset:17344
	s_waitcnt lgkmcnt(6)
	s_waitcnt vmcnt(47)
	v_mfma_f32_16x16x32_bf16 v[112:115], v[144:147], v[24:27], v[112:115]
	ds_read_b128 v[172:175], v196 offset:25792
	s_waitcnt lgkmcnt(6)
	v_mfma_f32_16x16x32_bf16 v[116:119], v[148:151], v[24:27], v[116:119]
	s_waitcnt lgkmcnt(5)
	v_mfma_f32_16x16x32_bf16 v[120:123], v[152:155], v[24:27], v[120:123]
	s_waitcnt lgkmcnt(4)
	v_mfma_f32_16x16x32_bf16 v[124:127], v[156:159], v[24:27], v[124:127]
	global_load_dwordx4 v[24:27], v193, s[60:61] offset:384
	s_waitcnt lgkmcnt(3)
	s_waitcnt vmcnt(47)
	v_mfma_f32_16x16x32_bf16 v[112:115], v[160:163], v[28:31], v[112:115]
	s_waitcnt lgkmcnt(2)
	v_mfma_f32_16x16x32_bf16 v[116:119], v[164:167], v[28:31], v[116:119]
	s_waitcnt lgkmcnt(1)
	v_mfma_f32_16x16x32_bf16 v[120:123], v[168:171], v[28:31], v[120:123]
	s_waitcnt lgkmcnt(0)
	v_mfma_f32_16x16x32_bf16 v[124:127], v[172:175], v[28:31], v[124:127]
	global_load_dwordx4 v[28:31], v193, s[60:61] offset:448
	s_nop 7
	v_pk_mul_f32 v[112:113], v[112:113], v[202:203]
	v_pk_mul_f32 v[114:115], v[114:115], v[202:203]
	v_pk_mul_f32 v[116:117], v[116:117], v[202:203]
	v_pk_mul_f32 v[118:119], v[118:119], v[202:203]
	v_pk_mul_f32 v[120:121], v[120:121], v[202:203]
	v_pk_mul_f32 v[122:123], v[122:123], v[202:203]
	v_pk_mul_f32 v[124:125], v[124:125], v[202:203]
	v_pk_mul_f32 v[126:127], v[126:127], v[202:203]
	ds_read_b128 v[144:147], v197 offset:0
	ds_read_b128 v[148:151], v197 offset:4352
	ds_read_b128 v[152:155], v197 offset:8704
	ds_read_b128 v[156:159], v197 offset:13056
	ds_read_b128 v[160:163], v197 offset:64
	ds_read_b128 v[164:167], v197 offset:4416
	ds_read_b128 v[168:171], v197 offset:8768
	s_waitcnt lgkmcnt(6)
	s_waitcnt vmcnt(47)
	v_mfma_f32_16x16x32_bf16 v[112:115], v[144:147], v[32:35], v[112:115]
	ds_read_b128 v[172:175], v197 offset:13120
	s_waitcnt lgkmcnt(6)
	v_mfma_f32_16x16x32_bf16 v[116:119], v[148:151], v[32:35], v[116:119]
	ds_read_b128 v[144:147], v197 offset:128
	s_waitcnt lgkmcnt(6)
	v_mfma_f32_16x16x32_bf16 v[120:123], v[152:155], v[32:35], v[120:123]
	ds_read_b128 v[148:151], v197 offset:4480
	s_waitcnt lgkmcnt(6)
	v_mfma_f32_16x16x32_bf16 v[124:127], v[156:159], v[32:35], v[124:127]
	global_load_dwordx4 v[32:35], v192, s[62:63]
	ds_read_b128 v[152:155], v197 offset:8832
	s_waitcnt lgkmcnt(6)
	s_waitcnt vmcnt(47)
	v_mfma_f32_16x16x32_bf16 v[112:115], v[160:163], v[36:39], v[112:115]
	ds_read_b128 v[156:159], v197 offset:13184
	s_waitcnt lgkmcnt(6)
	v_mfma_f32_16x16x32_bf16 v[116:119], v[164:167], v[36:39], v[116:119]
	ds_read_b128 v[160:163], v197 offset:192
	s_waitcnt lgkmcnt(6)
	v_mfma_f32_16x16x32_bf16 v[120:123], v[168:171], v[36:39], v[120:123]
	ds_read_b128 v[164:167], v197 offset:4544
	s_waitcnt lgkmcnt(6)
	v_mfma_f32_16x16x32_bf16 v[124:127], v[172:175], v[36:39], v[124:127]
	global_load_dwordx4 v[36:39], v192, s[62:63] offset:1024
	ds_read_b128 v[168:171], v197 offset:8896
	s_waitcnt lgkmcnt(6)
	s_waitcnt vmcnt(47)
	v_mfma_f32_16x16x32_bf16 v[112:115], v[144:147], v[40:43], v[112:115]
	ds_read_b128 v[172:175], v197 offset:13248
	s_waitcnt lgkmcnt(6)
	v_mfma_f32_16x16x32_bf16 v[116:119], v[148:151], v[40:43], v[116:119]
	s_waitcnt lgkmcnt(5)
	v_mfma_f32_16x16x32_bf16 v[120:123], v[152:155], v[40:43], v[120:123]
	s_waitcnt lgkmcnt(4)
	v_mfma_f32_16x16x32_bf16 v[124:127], v[156:159], v[40:43], v[124:127]
	global_load_dwordx4 v[40:43], v192, s[62:63] offset:2048
	s_waitcnt lgkmcnt(3)
	s_waitcnt vmcnt(47)
	v_mfma_f32_16x16x32_bf16 v[112:115], v[160:163], v[44:47], v[112:115]
	s_waitcnt lgkmcnt(2)
	v_mfma_f32_16x16x32_bf16 v[116:119], v[164:167], v[44:47], v[116:119]
	s_waitcnt lgkmcnt(1)
	v_mfma_f32_16x16x32_bf16 v[120:123], v[168:171], v[44:47], v[120:123]
	s_waitcnt lgkmcnt(0)
	v_mfma_f32_16x16x32_bf16 v[124:127], v[172:175], v[44:47], v[124:127]
	global_load_dwordx4 v[44:47], v192, s[62:63] offset:3072
	s_nop 7
	v_cvt_pk_bf16_f32 v160, v112, v113
	v_cvt_pk_bf16_f32 v161, v114, v115
	v_cvt_pk_bf16_f32 v162, v116, v117
	v_cvt_pk_bf16_f32 v163, v118, v119
	v_cvt_pk_bf16_f32 v164, v120, v121
	v_cvt_pk_bf16_f32 v165, v122, v123
	v_cvt_pk_bf16_f32 v166, v124, v125
	v_cvt_pk_bf16_f32 v167, v126, v127
	ds_write_b64 v214, v[160:161]
	ds_write_b64 v214, v[162:163] offset:32
	ds_write_b64 v214, v[164:165] offset:64
	ds_write_b64 v214, v[166:167] offset:96
	s_waitcnt lgkmcnt(0)
	ds_read_b128 v[144:147], v215
	ds_read_b128 v[148:151], v215 offset:1152
	s_waitcnt lgkmcnt(0)
	global_store_dwordx4 v195, v[144:147], s[68:69]
	global_store_dwordx4 v220, v[148:151], s[68:69]
	v_pk_mul_f32 v[80:81], v[80:81], v[204:205]
	v_pk_mul_f32 v[82:83], v[82:83], v[204:205]
	v_pk_mul_f32 v[84:85], v[84:85], v[204:205]
	v_pk_mul_f32 v[86:87], v[86:87], v[204:205]
	v_pk_mul_f32 v[88:89], v[88:89], v[204:205]
	v_pk_mul_f32 v[90:91], v[90:91], v[204:205]
	v_pk_mul_f32 v[92:93], v[92:93], v[204:205]
	v_pk_mul_f32 v[94:95], v[94:95], v[204:205]
	v_pk_mul_f32 v[96:97], v[96:97], v[204:205]
	v_pk_mul_f32 v[98:99], v[98:99], v[204:205]
	v_pk_mul_f32 v[100:101], v[100:101], v[204:205]
	v_pk_mul_f32 v[102:103], v[102:103], v[204:205]
	v_pk_mul_f32 v[104:105], v[104:105], v[204:205]
	v_pk_mul_f32 v[106:107], v[106:107], v[204:205]
	v_pk_mul_f32 v[108:109], v[108:109], v[204:205]
	v_pk_mul_f32 v[110:111], v[110:111], v[204:205]
	ds_read_b128 v[144:147], v197 offset:0
	ds_read_b128 v[148:151], v197 offset:4352
	ds_read_b128 v[152:155], v197 offset:8704
	ds_read_b128 v[156:159], v197 offset:13056
	ds_read_b128 v[160:163], v197 offset:64
	ds_read_b128 v[164:167], v197 offset:4416
	ds_read_b128 v[168:171], v197 offset:8768
	s_waitcnt lgkmcnt(6)
	s_waitcnt vmcnt(22)
	v_mfma_f32_16x16x32_bf16 v[80:83], v[48:51], v[144:147], v[80:83]
	v_mfma_f32_16x16x32_bf16 v[96:99], v[64:67], v[144:147], v[96:99]
	ds_read_b128 v[172:175], v197 offset:13120
	s_waitcnt lgkmcnt(6)
	v_mfma_f32_16x16x32_bf16 v[84:87], v[48:51], v[148:151], v[84:87]
	v_mfma_f32_16x16x32_bf16 v[100:103], v[64:67], v[148:151], v[100:103]
	ds_read_b128 v[144:147], v197 offset:128
	s_waitcnt lgkmcnt(6)
	v_mfma_f32_16x16x32_bf16 v[88:91], v[48:51], v[152:155], v[88:91]
	v_mfma_f32_16x16x32_bf16 v[104:107], v[64:67], v[152:155], v[104:107]
	ds_read_b128 v[148:151], v197 offset:4480
	s_waitcnt lgkmcnt(6)
	v_mfma_f32_16x16x32_bf16 v[92:95], v[48:51], v[156:159], v[92:95]
	v_mfma_f32_16x16x32_bf16 v[108:111], v[64:67], v[156:159], v[108:111]
	global_load_dwordx4 v[48:51], v192, s[64:65] offset:-4096
	global_load_dwordx4 v[64:67], v192, s[64:65]
	ds_read_b128 v[152:155], v197 offset:8832
	s_waitcnt lgkmcnt(6)
	s_waitcnt vmcnt(22)
	v_mfma_f32_16x16x32_bf16 v[80:83], v[52:55], v[160:163], v[80:83]
	v_mfma_f32_16x16x32_bf16 v[96:99], v[68:71], v[160:163], v[96:99]
	ds_read_b128 v[156:159], v197 offset:13184
	s_waitcnt lgkmcnt(6)
	v_mfma_f32_16x16x32_bf16 v[84:87], v[52:55], v[164:167], v[84:87]
	v_mfma_f32_16x16x32_bf16 v[100:103], v[68:71], v[164:167], v[100:103]
	ds_read_b128 v[160:163], v197 offset:192
	s_waitcnt lgkmcnt(6)
	v_mfma_f32_16x16x32_bf16 v[88:91], v[52:55], v[168:171], v[88:91]
	v_mfma_f32_16x16x32_bf16 v[104:107], v[68:71], v[168:171], v[104:107]
	ds_read_b128 v[164:167], v197 offset:4544
	s_waitcnt lgkmcnt(6)
	v_mfma_f32_16x16x32_bf16 v[92:95], v[52:55], v[172:175], v[92:95]
	v_mfma_f32_16x16x32_bf16 v[108:111], v[68:71], v[172:175], v[108:111]
	global_load_dwordx4 v[52:55], v192, s[64:65] offset:-3072
	global_load_dwordx4 v[68:71], v192, s[64:65] offset:1024
	ds_read_b128 v[168:171], v197 offset:8896
	s_waitcnt lgkmcnt(6)
	s_waitcnt vmcnt(22)
	v_mfma_f32_16x16x32_bf16 v[80:83], v[56:59], v[144:147], v[80:83]
	v_mfma_f32_16x16x32_bf16 v[96:99], v[72:75], v[144:147], v[96:99]
	ds_read_b128 v[172:175], v197 offset:13248
	s_waitcnt lgkmcnt(6)
	v_mfma_f32_16x16x32_bf16 v[84:87], v[56:59], v[148:151], v[84:87]
	v_mfma_f32_16x16x32_bf16 v[100:103], v[72:75], v[148:151], v[100:103]
	s_waitcnt lgkmcnt(5)
	v_mfma_f32_16x16x32_bf16 v[88:91], v[56:59], v[152:155], v[88:91]
	v_mfma_f32_16x16x32_bf16 v[104:107], v[72:75], v[152:155], v[104:107]
	s_waitcnt lgkmcnt(4)
	v_mfma_f32_16x16x32_bf16 v[92:95], v[56:59], v[156:159], v[92:95]
	v_mfma_f32_16x16x32_bf16 v[108:111], v[72:75], v[156:159], v[108:111]
	global_load_dwordx4 v[56:59], v192, s[64:65] offset:-2048
	global_load_dwordx4 v[72:75], v192, s[64:65] offset:2048
	s_waitcnt lgkmcnt(3)
	s_waitcnt vmcnt(22)
	v_mfma_f32_16x16x32_bf16 v[80:83], v[60:63], v[160:163], v[80:83]
	v_mfma_f32_16x16x32_bf16 v[96:99], v[76:79], v[160:163], v[96:99]
	s_waitcnt lgkmcnt(2)
	v_mfma_f32_16x16x32_bf16 v[84:87], v[60:63], v[164:167], v[84:87]
	v_mfma_f32_16x16x32_bf16 v[100:103], v[76:79], v[164:167], v[100:103]
	s_waitcnt lgkmcnt(1)
	v_mfma_f32_16x16x32_bf16 v[88:91], v[60:63], v[168:171], v[88:91]
	v_mfma_f32_16x16x32_bf16 v[104:107], v[76:79], v[168:171], v[104:107]
	s_waitcnt lgkmcnt(0)
	v_mfma_f32_16x16x32_bf16 v[92:95], v[60:63], v[172:175], v[92:95]
	v_mfma_f32_16x16x32_bf16 v[108:111], v[76:79], v[172:175], v[108:111]
	global_load_dwordx4 v[60:63], v192, s[64:65] offset:-1024
	global_load_dwordx4 v[76:79], v192, s[64:65] offset:3072
	s_nop 7
	v_cvt_pk_bf16_f32 v144, v80, v81
	v_cvt_pk_bf16_f32 v145, v82, v83
	ds_write_b64 v200, v[144:145] offset:0
	v_cvt_pk_bf16_f32 v148, v84, v85
	v_cvt_pk_bf16_f32 v149, v86, v87
	ds_write_b64 v200, v[148:149] offset:8448
	v_cvt_pk_bf16_f32 v152, v88, v89
	v_cvt_pk_bf16_f32 v153, v90, v91
	ds_write_b64 v200, v[152:153] offset:16896
	v_cvt_pk_bf16_f32 v156, v92, v93
	v_cvt_pk_bf16_f32 v157, v94, v95
	ds_write_b64 v200, v[156:157] offset:25344
	v_cvt_pk_bf16_f32 v160, v96, v97
	v_cvt_pk_bf16_f32 v161, v98, v99
	ds_write_b64 v200, v[160:161] offset:32
	v_cvt_pk_bf16_f32 v164, v100, v101
	v_cvt_pk_bf16_f32 v165, v102, v103
	ds_write_b64 v200, v[164:165] offset:8480
	v_cvt_pk_bf16_f32 v168, v104, v105
	v_cvt_pk_bf16_f32 v169, v106, v107
	ds_write_b64 v200, v[168:169] offset:16928
	v_cvt_pk_bf16_f32 v172, v108, v109
	v_cvt_pk_bf16_f32 v173, v110, v111
	ds_write_b64 v200, v[172:173] offset:25376
	s_waitcnt vmcnt(46)
	ds_write_b128 v201, v[222:225]
	ds_write_b128 v201, v[226:229] offset:128
	v_add_u32_e32 v196, s80, v196
	v_subrev_u32_e32 v200, s80, v200
	v_add_u32_e32 v197, s81, v197
	v_subrev_u32_e32 v201, s81, v201
	s_sub_u32 s80, 0, s80
	s_sub_u32 s81, 0, s81
	s_add_u32 s68, s68, 0x80000
	s_addc_u32 s69, s69, 0
	s_add_u32 s70, s70, 1
	s_cmp_lt_u32 s70, 31
	s_cselect_b32 s83, 1, 0
	s_lshl_b32 s76, s83, 16
	s_add_u32 s64, s64, s76
	s_addc_u32 s65, s65, 0
	s_cmp_lt_u32 s70, 30
	s_cselect_b32 s83, 1, 0
	s_lshl_b32 s76, s83, 18
	s_add_u32 s60, s60, s76
	s_addc_u32 s61, s61, 0
	s_lshl_b32 s76, s83, 15
	s_add_u32 s62, s62, s76
	s_addc_u32 s63, s63, 0
	s_lshl_b32 s76, s83, 8
	s_add_u32 s66, s66, s76
	s_addc_u32 s67, s67, 0
	s_waitcnt lgkmcnt(0)
	s_barrier
	global_load_dwordx4 v[222:225], v194, s[66:67]
	global_load_dwordx4 v[226:229], v194, s[66:67] offset:128
	ds_read_b128 v[144:147], v196 offset:0
	ds_read_b128 v[148:151], v196 offset:8448
	ds_read_b128 v[152:155], v196 offset:16896
	ds_read_b128 v[156:159], v196 offset:25344
	ds_read_b128 v[160:163], v196 offset:64
	ds_read_b128 v[164:167], v196 offset:8512
	ds_read_b128 v[168:171], v196 offset:16960
	s_waitcnt lgkmcnt(6)
	s_waitcnt vmcnt(47)
	v_mfma_f32_16x16x32_bf16 v[112:115], v[144:147], v[230:233], 0
	ds_read_b128 v[172:175], v196 offset:25408
	s_waitcnt lgkmcnt(6)
	v_mfma_f32_16x16x32_bf16 v[116:119], v[148:151], v[230:233], 0
	ds_read_b128 v[144:147], v196 offset:128
	s_waitcnt lgkmcnt(6)
	v_mfma_f32_16x16x32_bf16 v[120:123], v[152:155], v[230:233], 0
	ds_read_b128 v[148:151], v196 offset:8576
	s_waitcnt lgkmcnt(6)
	v_mfma_f32_16x16x32_bf16 v[124:127], v[156:159], v[230:233], 0
	global_load_dwordx4 v[230:233], v193, s[60:61]
	ds_read_b128 v[152:155], v196 offset:17024
	s_waitcnt lgkmcnt(6)
	s_waitcnt vmcnt(47)
	v_mfma_f32_16x16x32_bf16 v[112:115], v[160:163], v[234:237], v[112:115]
	ds_read_b128 v[156:159], v196 offset:25472
	s_waitcnt lgkmcnt(6)
	v_mfma_f32_16x16x32_bf16 v[116:119], v[164:167], v[234:237], v[116:119]
	ds_read_b128 v[160:163], v196 offset:192
	s_waitcnt lgkmcnt(6)
	v_mfma_f32_16x16x32_bf16 v[120:123], v[168:171], v[234:237], v[120:123]
	ds_read_b128 v[164:167], v196 offset:8640
	s_waitcnt lgkmcnt(6)
	v_mfma_f32_16x16x32_bf16 v[124:127], v[172:175], v[234:237], v[124:127]
	global_load_dwordx4 v[234:237], v193, s[60:61] offset:64
	ds_read_b128 v[168:171], v196 offset:17088
	s_waitcnt lgkmcnt(6)
	s_waitcnt vmcnt(47)
	v_mfma_f32_16x16x32_bf16 v[112:115], v[144:147], v[238:241], v[112:115]
	ds_read_b128 v[172:175], v196 offset:25536
	s_waitcnt lgkmcnt(6)
	v_mfma_f32_16x16x32_bf16 v[116:119], v[148:151], v[238:241], v[116:119]
	ds_read_b128 v[144:147], v196 offset:256
	s_waitcnt lgkmcnt(6)
	v_mfma_f32_16x16x32_bf16 v[120:123], v[152:155], v[238:241], v[120:123]
	ds_read_b128 v[148:151], v196 offset:8704
	s_waitcnt lgkmcnt(6)
	v_mfma_f32_16x16x32_bf16 v[124:127], v[156:159], v[238:241], v[124:127]
	global_load_dwordx4 v[238:241], v193, s[60:61] offset:128
	ds_read_b128 v[152:155], v196 offset:17152
	s_waitcnt lgkmcnt(6)
	s_waitcnt vmcnt(47)
	v_mfma_f32_16x16x32_bf16 v[112:115], v[160:163], v[242:245], v[112:115]
	ds_read_b128 v[156:159], v196 offset:25600
	s_waitcnt lgkmcnt(6)
	v_mfma_f32_16x16x32_bf16 v[116:119], v[164:167], v[242:245], v[116:119]
	ds_read_b128 v[160:163], v196 offset:320
	s_waitcnt lgkmcnt(6)
	v_mfma_f32_16x16x32_bf16 v[120:123], v[168:171], v[242:245], v[120:123]
	ds_read_b128 v[164:167], v196 offset:8768
	s_waitcnt lgkmcnt(6)
	v_mfma_f32_16x16x32_bf16 v[124:127], v[172:175], v[242:245], v[124:127]
	global_load_dwordx4 v[242:245], v193, s[60:61] offset:192
	ds_read_b128 v[168:171], v196 offset:17216
	s_waitcnt lgkmcnt(6)
	s_waitcnt vmcnt(47)
	v_mfma_f32_16x16x32_bf16 v[112:115], v[144:147], v[246:249], v[112:115]
	ds_read_b128 v[172:175], v196 offset:25664
	s_waitcnt lgkmcnt(6)
	v_mfma_f32_16x16x32_bf16 v[116:119], v[148:151], v[246:249], v[116:119]
	ds_read_b128 v[144:147], v196 offset:384
	s_waitcnt lgkmcnt(6)
	v_mfma_f32_16x16x32_bf16 v[120:123], v[152:155], v[246:249], v[120:123]
	ds_read_b128 v[148:151], v196 offset:8832
	s_waitcnt lgkmcnt(6)
	v_mfma_f32_16x16x32_bf16 v[124:127], v[156:159], v[246:249], v[124:127]
	global_load_dwordx4 v[246:249], v193, s[60:61] offset:256
	ds_read_b128 v[152:155], v196 offset:17280
	s_waitcnt lgkmcnt(6)
	s_waitcnt vmcnt(47)
	v_mfma_f32_16x16x32_bf16 v[112:115], v[160:163], v[250:253], v[112:115]
	ds_read_b128 v[156:159], v196 offset:25728
	s_waitcnt lgkmcnt(6)
	v_mfma_f32_16x16x32_bf16 v[116:119], v[164:167], v[250:253], v[116:119]
	ds_read_b128 v[160:163], v196 offset:448
	s_waitcnt lgkmcnt(6)
	v_mfma_f32_16x16x32_bf16 v[120:123], v[168:171], v[250:253], v[120:123]
	ds_read_b128 v[164:167], v196 offset:8896
	s_waitcnt lgkmcnt(6)
	v_mfma_f32_16x16x32_bf16 v[124:127], v[172:175], v[250:253], v[124:127]
	global_load_dwordx4 v[250:253], v193, s[60:61] offset:320
	ds_read_b128 v[168:171], v196 offset:17344
	s_waitcnt lgkmcnt(6)
	s_waitcnt vmcnt(47)
	v_mfma_f32_16x16x32_bf16 v[112:115], v[144:147], v[184:187], v[112:115]
	ds_read_b128 v[172:175], v196 offset:25792
	s_waitcnt lgkmcnt(6)
	v_mfma_f32_16x16x32_bf16 v[116:119], v[148:151], v[184:187], v[116:119]
	s_waitcnt lgkmcnt(5)
	v_mfma_f32_16x16x32_bf16 v[120:123], v[152:155], v[184:187], v[120:123]
	s_waitcnt lgkmcnt(4)
	v_mfma_f32_16x16x32_bf16 v[124:127], v[156:159], v[184:187], v[124:127]
	global_load_dwordx4 v[184:187], v193, s[60:61] offset:384
	s_waitcnt lgkmcnt(3)
	s_waitcnt vmcnt(47)
	v_mfma_f32_16x16x32_bf16 v[112:115], v[160:163], v[188:191], v[112:115]
	s_waitcnt lgkmcnt(2)
	v_mfma_f32_16x16x32_bf16 v[116:119], v[164:167], v[188:191], v[116:119]
	s_waitcnt lgkmcnt(1)
	v_mfma_f32_16x16x32_bf16 v[120:123], v[168:171], v[188:191], v[120:123]
	s_waitcnt lgkmcnt(0)
	v_mfma_f32_16x16x32_bf16 v[124:127], v[172:175], v[188:191], v[124:127]
	global_load_dwordx4 v[188:191], v193, s[60:61] offset:448
	s_nop 7
	v_pk_mul_f32 v[112:113], v[112:113], v[202:203]
	v_pk_mul_f32 v[114:115], v[114:115], v[202:203]
	v_pk_mul_f32 v[116:117], v[116:117], v[202:203]
	v_pk_mul_f32 v[118:119], v[118:119], v[202:203]
	v_pk_mul_f32 v[120:121], v[120:121], v[202:203]
	v_pk_mul_f32 v[122:123], v[122:123], v[202:203]
	v_pk_mul_f32 v[124:125], v[124:125], v[202:203]
	v_pk_mul_f32 v[126:127], v[126:127], v[202:203]
	ds_read_b128 v[144:147], v197 offset:0
	ds_read_b128 v[148:151], v197 offset:4352
	ds_read_b128 v[152:155], v197 offset:8704
	ds_read_b128 v[156:159], v197 offset:13056
	ds_read_b128 v[160:163], v197 offset:64
	ds_read_b128 v[164:167], v197 offset:4416
	ds_read_b128 v[168:171], v197 offset:8768
	s_waitcnt lgkmcnt(6)
	s_waitcnt vmcnt(47)
	v_mfma_f32_16x16x32_bf16 v[112:115], v[144:147], v[128:131], v[112:115]
	ds_read_b128 v[172:175], v197 offset:13120
	s_waitcnt lgkmcnt(6)
	v_mfma_f32_16x16x32_bf16 v[116:119], v[148:151], v[128:131], v[116:119]
	ds_read_b128 v[144:147], v197 offset:128
	s_waitcnt lgkmcnt(6)
	v_mfma_f32_16x16x32_bf16 v[120:123], v[152:155], v[128:131], v[120:123]
	ds_read_b128 v[148:151], v197 offset:4480
	s_waitcnt lgkmcnt(6)
	v_mfma_f32_16x16x32_bf16 v[124:127], v[156:159], v[128:131], v[124:127]
	global_load_dwordx4 v[128:131], v192, s[62:63]
	ds_read_b128 v[152:155], v197 offset:8832
	s_waitcnt lgkmcnt(6)
	s_waitcnt vmcnt(47)
	v_mfma_f32_16x16x32_bf16 v[112:115], v[160:163], v[132:135], v[112:115]
	ds_read_b128 v[156:159], v197 offset:13184
	s_waitcnt lgkmcnt(6)
	v_mfma_f32_16x16x32_bf16 v[116:119], v[164:167], v[132:135], v[116:119]
	ds_read_b128 v[160:163], v197 offset:192
	s_waitcnt lgkmcnt(6)
	v_mfma_f32_16x16x32_bf16 v[120:123], v[168:171], v[132:135], v[120:123]
	ds_read_b128 v[164:167], v197 offset:4544
	s_waitcnt lgkmcnt(6)
	v_mfma_f32_16x16x32_bf16 v[124:127], v[172:175], v[132:135], v[124:127]
	global_load_dwordx4 v[132:135], v192, s[62:63] offset:1024
	ds_read_b128 v[168:171], v197 offset:8896
	s_waitcnt lgkmcnt(6)
	s_waitcnt vmcnt(47)
	v_mfma_f32_16x16x32_bf16 v[112:115], v[144:147], v[136:139], v[112:115]
	ds_read_b128 v[172:175], v197 offset:13248
	s_waitcnt lgkmcnt(6)
	v_mfma_f32_16x16x32_bf16 v[116:119], v[148:151], v[136:139], v[116:119]
	s_waitcnt lgkmcnt(5)
	v_mfma_f32_16x16x32_bf16 v[120:123], v[152:155], v[136:139], v[120:123]
	s_waitcnt lgkmcnt(4)
	v_mfma_f32_16x16x32_bf16 v[124:127], v[156:159], v[136:139], v[124:127]
	global_load_dwordx4 v[136:139], v192, s[62:63] offset:2048
	s_waitcnt lgkmcnt(3)
	s_waitcnt vmcnt(47)
	v_mfma_f32_16x16x32_bf16 v[112:115], v[160:163], v[140:143], v[112:115]
	s_waitcnt lgkmcnt(2)
	v_mfma_f32_16x16x32_bf16 v[116:119], v[164:167], v[140:143], v[116:119]
	s_waitcnt lgkmcnt(1)
	v_mfma_f32_16x16x32_bf16 v[120:123], v[168:171], v[140:143], v[120:123]
	s_waitcnt lgkmcnt(0)
	v_mfma_f32_16x16x32_bf16 v[124:127], v[172:175], v[140:143], v[124:127]
	global_load_dwordx4 v[140:143], v192, s[62:63] offset:3072
	s_nop 7
	v_cvt_pk_bf16_f32 v160, v112, v113
	v_cvt_pk_bf16_f32 v161, v114, v115
	v_cvt_pk_bf16_f32 v162, v116, v117
	v_cvt_pk_bf16_f32 v163, v118, v119
	v_cvt_pk_bf16_f32 v164, v120, v121
	v_cvt_pk_bf16_f32 v165, v122, v123
	v_cvt_pk_bf16_f32 v166, v124, v125
	v_cvt_pk_bf16_f32 v167, v126, v127
	ds_write_b64 v214, v[160:161]
	ds_write_b64 v214, v[162:163] offset:32
	ds_write_b64 v214, v[164:165] offset:64
	ds_write_b64 v214, v[166:167] offset:96
	s_waitcnt lgkmcnt(0)
	ds_read_b128 v[144:147], v215
	ds_read_b128 v[148:151], v215 offset:1152
	s_waitcnt lgkmcnt(0)
	global_store_dwordx4 v195, v[144:147], s[68:69]
	global_store_dwordx4 v220, v[148:151], s[68:69]
	v_pk_mul_f32 v[80:81], v[80:81], v[204:205]
	v_pk_mul_f32 v[82:83], v[82:83], v[204:205]
	v_pk_mul_f32 v[84:85], v[84:85], v[204:205]
	v_pk_mul_f32 v[86:87], v[86:87], v[204:205]
	v_pk_mul_f32 v[88:89], v[88:89], v[204:205]
	v_pk_mul_f32 v[90:91], v[90:91], v[204:205]
	v_pk_mul_f32 v[92:93], v[92:93], v[204:205]
	v_pk_mul_f32 v[94:95], v[94:95], v[204:205]
	v_pk_mul_f32 v[96:97], v[96:97], v[204:205]
	v_pk_mul_f32 v[98:99], v[98:99], v[204:205]
	v_pk_mul_f32 v[100:101], v[100:101], v[204:205]
	v_pk_mul_f32 v[102:103], v[102:103], v[204:205]
	v_pk_mul_f32 v[104:105], v[104:105], v[204:205]
	v_pk_mul_f32 v[106:107], v[106:107], v[204:205]
	v_pk_mul_f32 v[108:109], v[108:109], v[204:205]
	v_pk_mul_f32 v[110:111], v[110:111], v[204:205]
	ds_read_b128 v[144:147], v197 offset:0
	ds_read_b128 v[148:151], v197 offset:4352
	ds_read_b128 v[152:155], v197 offset:8704
	ds_read_b128 v[156:159], v197 offset:13056
	ds_read_b128 v[160:163], v197 offset:64
	ds_read_b128 v[164:167], v197 offset:4416
	ds_read_b128 v[168:171], v197 offset:8768
	s_waitcnt lgkmcnt(6)
	s_waitcnt vmcnt(22)
	v_mfma_f32_16x16x32_bf16 v[80:83], v[48:51], v[144:147], v[80:83]
	v_mfma_f32_16x16x32_bf16 v[96:99], v[64:67], v[144:147], v[96:99]
	ds_read_b128 v[172:175], v197 offset:13120
	s_waitcnt lgkmcnt(6)
	v_mfma_f32_16x16x32_bf16 v[84:87], v[48:51], v[148:151], v[84:87]
	v_mfma_f32_16x16x32_bf16 v[100:103], v[64:67], v[148:151], v[100:103]
	ds_read_b128 v[144:147], v197 offset:128
	s_waitcnt lgkmcnt(6)
	v_mfma_f32_16x16x32_bf16 v[88:91], v[48:51], v[152:155], v[88:91]
	v_mfma_f32_16x16x32_bf16 v[104:107], v[64:67], v[152:155], v[104:107]
	ds_read_b128 v[148:151], v197 offset:4480
	s_waitcnt lgkmcnt(6)
	v_mfma_f32_16x16x32_bf16 v[92:95], v[48:51], v[156:159], v[92:95]
	v_mfma_f32_16x16x32_bf16 v[108:111], v[64:67], v[156:159], v[108:111]
	global_load_dwordx4 v[48:51], v192, s[64:65] offset:-4096
	global_load_dwordx4 v[64:67], v192, s[64:65]
	ds_read_b128 v[152:155], v197 offset:8832
	s_waitcnt lgkmcnt(6)
	s_waitcnt vmcnt(22)
	v_mfma_f32_16x16x32_bf16 v[80:83], v[52:55], v[160:163], v[80:83]
	v_mfma_f32_16x16x32_bf16 v[96:99], v[68:71], v[160:163], v[96:99]
	ds_read_b128 v[156:159], v197 offset:13184
	s_waitcnt lgkmcnt(6)
	v_mfma_f32_16x16x32_bf16 v[84:87], v[52:55], v[164:167], v[84:87]
	v_mfma_f32_16x16x32_bf16 v[100:103], v[68:71], v[164:167], v[100:103]
	ds_read_b128 v[160:163], v197 offset:192
	s_waitcnt lgkmcnt(6)
	v_mfma_f32_16x16x32_bf16 v[88:91], v[52:55], v[168:171], v[88:91]
	v_mfma_f32_16x16x32_bf16 v[104:107], v[68:71], v[168:171], v[104:107]
	ds_read_b128 v[164:167], v197 offset:4544
	s_waitcnt lgkmcnt(6)
	v_mfma_f32_16x16x32_bf16 v[92:95], v[52:55], v[172:175], v[92:95]
	v_mfma_f32_16x16x32_bf16 v[108:111], v[68:71], v[172:175], v[108:111]
	global_load_dwordx4 v[52:55], v192, s[64:65] offset:-3072
	global_load_dwordx4 v[68:71], v192, s[64:65] offset:1024
	ds_read_b128 v[168:171], v197 offset:8896
	s_waitcnt lgkmcnt(6)
	s_waitcnt vmcnt(22)
	v_mfma_f32_16x16x32_bf16 v[80:83], v[56:59], v[144:147], v[80:83]
	v_mfma_f32_16x16x32_bf16 v[96:99], v[72:75], v[144:147], v[96:99]
	ds_read_b128 v[172:175], v197 offset:13248
	s_waitcnt lgkmcnt(6)
	v_mfma_f32_16x16x32_bf16 v[84:87], v[56:59], v[148:151], v[84:87]
	v_mfma_f32_16x16x32_bf16 v[100:103], v[72:75], v[148:151], v[100:103]
	s_waitcnt lgkmcnt(5)
	v_mfma_f32_16x16x32_bf16 v[88:91], v[56:59], v[152:155], v[88:91]
	v_mfma_f32_16x16x32_bf16 v[104:107], v[72:75], v[152:155], v[104:107]
	s_waitcnt lgkmcnt(4)
	v_mfma_f32_16x16x32_bf16 v[92:95], v[56:59], v[156:159], v[92:95]
	v_mfma_f32_16x16x32_bf16 v[108:111], v[72:75], v[156:159], v[108:111]
	global_load_dwordx4 v[56:59], v192, s[64:65] offset:-2048
	global_load_dwordx4 v[72:75], v192, s[64:65] offset:2048
	s_waitcnt lgkmcnt(3)
	s_waitcnt vmcnt(22)
	v_mfma_f32_16x16x32_bf16 v[80:83], v[60:63], v[160:163], v[80:83]
	v_mfma_f32_16x16x32_bf16 v[96:99], v[76:79], v[160:163], v[96:99]
	s_waitcnt lgkmcnt(2)
	v_mfma_f32_16x16x32_bf16 v[84:87], v[60:63], v[164:167], v[84:87]
	v_mfma_f32_16x16x32_bf16 v[100:103], v[76:79], v[164:167], v[100:103]
	s_waitcnt lgkmcnt(1)
	v_mfma_f32_16x16x32_bf16 v[88:91], v[60:63], v[168:171], v[88:91]
	v_mfma_f32_16x16x32_bf16 v[104:107], v[76:79], v[168:171], v[104:107]
	s_waitcnt lgkmcnt(0)
	v_mfma_f32_16x16x32_bf16 v[92:95], v[60:63], v[172:175], v[92:95]
	v_mfma_f32_16x16x32_bf16 v[108:111], v[76:79], v[172:175], v[108:111]
	global_load_dwordx4 v[60:63], v192, s[64:65] offset:-1024
	global_load_dwordx4 v[76:79], v192, s[64:65] offset:3072
	s_nop 7
	v_cvt_pk_bf16_f32 v144, v80, v81
	v_cvt_pk_bf16_f32 v145, v82, v83
	ds_write_b64 v200, v[144:145] offset:0
	v_cvt_pk_bf16_f32 v148, v84, v85
	v_cvt_pk_bf16_f32 v149, v86, v87
	ds_write_b64 v200, v[148:149] offset:8448
	v_cvt_pk_bf16_f32 v152, v88, v89
	v_cvt_pk_bf16_f32 v153, v90, v91
	ds_write_b64 v200, v[152:153] offset:16896
	v_cvt_pk_bf16_f32 v156, v92, v93
	v_cvt_pk_bf16_f32 v157, v94, v95
	ds_write_b64 v200, v[156:157] offset:25344
	v_cvt_pk_bf16_f32 v160, v96, v97
	v_cvt_pk_bf16_f32 v161, v98, v99
	ds_write_b64 v200, v[160:161] offset:32
	v_cvt_pk_bf16_f32 v164, v100, v101
	v_cvt_pk_bf16_f32 v165, v102, v103
	ds_write_b64 v200, v[164:165] offset:8480
	v_cvt_pk_bf16_f32 v168, v104, v105
	v_cvt_pk_bf16_f32 v169, v106, v107
	ds_write_b64 v200, v[168:169] offset:16928
	v_cvt_pk_bf16_f32 v172, v108, v109
	v_cvt_pk_bf16_f32 v173, v110, v111
	ds_write_b64 v200, v[172:173] offset:25376
	s_waitcnt vmcnt(46)
	ds_write_b128 v201, v[176:179]
	ds_write_b128 v201, v[180:183] offset:128
	v_add_u32_e32 v196, s80, v196
	v_subrev_u32_e32 v200, s80, v200
	v_add_u32_e32 v197, s81, v197
	v_subrev_u32_e32 v201, s81, v201
	s_sub_u32 s80, 0, s80
	s_sub_u32 s81, 0, s81
	s_add_u32 s68, s68, 0x80000
	s_addc_u32 s69, s69, 0
	s_add_u32 s70, s70, 1
	s_cmp_lt_u32 s70, 31
	s_cselect_b32 s83, 1, 0
	s_lshl_b32 s76, s83, 16
	s_add_u32 s64, s64, s76
	s_addc_u32 s65, s65, 0
	s_cmp_lt_u32 s70, 30
	s_cselect_b32 s83, 1, 0
	s_lshl_b32 s76, s83, 18
	s_add_u32 s60, s60, s76
	s_addc_u32 s61, s61, 0
	s_lshl_b32 s76, s83, 15
	s_add_u32 s62, s62, s76
	s_addc_u32 s63, s63, 0
	s_lshl_b32 s76, s83, 8
	s_add_u32 s66, s66, s76
	s_addc_u32 s67, s67, 0
	s_waitcnt lgkmcnt(0)
	s_barrier
	s_cmp_lt_u32 s70, 32
	s_cbranch_scc1 .Lscan_chunk
	s_setprio 0
	s_waitcnt vmcnt(0)
	global_store_dword v206, v80, s[44:45]
	global_store_dword v207, v81, s[44:45]
	global_store_dword v208, v82, s[44:45]
	global_store_dword v209, v83, s[44:45]
	global_store_dword v206, v84, s[44:45] offset:64
	global_store_dword v207, v85, s[44:45] offset:64
	global_store_dword v208, v86, s[44:45] offset:64
	global_store_dword v209, v87, s[44:45] offset:64
	global_store_dword v206, v88, s[44:45] offset:128
	global_store_dword v207, v89, s[44:45] offset:128
	global_store_dword v208, v90, s[44:45] offset:128
	global_store_dword v209, v91, s[44:45] offset:128
	global_store_dword v206, v92, s[44:45] offset:192
	global_store_dword v207, v93, s[44:45] offset:192
	global_store_dword v208, v94, s[44:45] offset:192
	global_store_dword v209, v95, s[44:45] offset:192
	global_store_dword v206, v96, s[46:47]
	global_store_dword v207, v97, s[46:47]
	global_store_dword v208, v98, s[46:47]
	global_store_dword v209, v99, s[46:47]
	global_store_dword v206, v100, s[46:47] offset:64
	global_store_dword v207, v101, s[46:47] offset:64
	global_store_dword v208, v102, s[46:47] offset:64
	global_store_dword v209, v103, s[46:47] offset:64
	global_store_dword v206, v104, s[46:47] offset:128
	global_store_dword v207, v105, s[46:47] offset:128
	global_store_dword v208, v106, s[46:47] offset:128
	global_store_dword v209, v107, s[46:47] offset:128
	global_store_dword v206, v108, s[46:47] offset:192
	global_store_dword v207, v109, s[46:47] offset:192
	global_store_dword v208, v110, s[46:47] offset:192
	global_store_dword v209, v111, s[46:47] offset:192
